# P2: odd waves start one K-step (1.7 us) late so each even/odd wave pair reads the same K/V block together (L1 sharing); WG barrier where the GQA part begins
# speedup vs baseline: 1.0077x; 1.0019x over previous
.LBB0_213:
	s_cmp_lt_i32 s74, 3
	s_cselect_b64 s[0:1], -1, 0
	s_cmp_gt_i32 s75, 2
	s_cselect_b64 s[4:5], -1, 0
	s_and_b64 s[0:1], s[0:1], s[4:5]
	s_andn2_b64 vcc, exec, s[0:1]
	s_cbranch_vccnz .LBB0_354
	s_lshl_b32 s3, s18, 3
	s_abs_i32 s0, s3
	v_cvt_f32_u32_e32 v1, s0
	s_sub_i32 s5, 0, s0
	s_add_i32 s1, s3, 0x27ff
	v_writelane_b32 v243, s76, 1
	v_rcp_iflag_f32_e32 v1, v1
	s_xor_b32 s4, s1, s3
	s_abs_i32 s1, s1
	v_writelane_b32 v243, s88, 2
	v_mul_f32_e32 v1, 0x4f7ffffe, v1
	v_cvt_u32_f32_e32 v1, v1
	v_writelane_b32 v243, s89, 3
	v_writelane_b32 v243, s86, 4
	s_ashr_i32 s4, s4, 31
	v_readfirstlane_b32 s6, v1
	s_mul_i32 s5, s5, s6
	s_mul_hi_u32 s5, s6, s5
	s_add_i32 s6, s6, s5
	s_mul_hi_u32 s5, s1, s6
	s_mul_i32 s6, s5, s0
	s_sub_i32 s1, s1, s6
	v_writelane_b32 v243, s87, 5
	s_add_i32 s7, s5, 1
	s_sub_i32 s6, s1, s0
	v_writelane_b32 v243, s81, 6
	s_cmp_ge_u32 s1, s0
	v_writelane_b32 v243, s84, 7
	s_cselect_b32 s5, s7, s5
	s_cselect_b32 s1, s6, s1
	v_writelane_b32 v243, s85, 8
	s_add_i32 s6, s5, 1
	v_writelane_b32 v243, s90, 9
	s_cmp_ge_u32 s1, s0
	s_cselect_b32 s0, s6, s5
	v_writelane_b32 v243, s91, 10
	v_writelane_b32 v243, s68, 11
	s_load_dwordx2 s[22:23], s[68:69], 24
	s_waitcnt lgkmcnt(0)
	s_xor_b32 s0, s0, s4
	s_sub_i32 s19, s0, s4
	s_cmp_lt_i32 s19, 1
	s_mov_b32 s25, 0
	v_writelane_b32 v243, s69, 12
	s_cbranch_scc1 .LBB0_300
	v_bfe_u32 v1, v0, 4, 2
	v_xor_b32_e32 v4, v1, v0
	s_add_u32 s0, s72, 0x2b00000
	v_lshlrev_b32_e32 v4, 3, v4
	v_writelane_b32 v243, s0, 13
	s_addc_u32 s0, s73, 0
	v_and_b32_e32 v106, 0x78, v4
	v_bitop3_b32 v4, v1, v0, 4 bitop3:0x36
	v_writelane_b32 v243, s0, 14
	s_add_u32 s0, s72, 0x5b00000
	v_lshlrev_b32_e32 v4, 3, v4
	v_writelane_b32 v243, s0, 16
	s_addc_u32 s0, s73, 0
	v_and_b32_e32 v108, 0x78, v4
	v_bitop3_b32 v4, v1, v0, 8 bitop3:0x36
	v_writelane_b32 v243, s0, 18
	s_add_u32 s0, s72, 0x8b00000
	v_lshlrev_b32_e32 v4, 3, v4
	v_writelane_b32 v243, s0, 20
	s_addc_u32 s0, s73, 0
	v_and_b32_e32 v110, 0x78, v4
	v_bitop3_b32 v4, v1, v0, 12 bitop3:0x36
	v_writelane_b32 v243, s0, 21
	s_add_u32 s0, s72, 0xbb00000
	v_lshlrev_b32_e32 v4, 3, v4
	v_writelane_b32 v243, s0, 22
	s_addc_u32 s0, s73, 0
	v_and_b32_e32 v112, 0x78, v4
	v_bitop3_b32 v4, v1, v0, 20 bitop3:0x36
	v_writelane_b32 v243, s0, 23
	s_add_u32 s0, s72, 0xdb00000
	v_lshlrev_b32_e32 v4, 3, v4
	v_writelane_b32 v243, s0, 24
	s_addc_u32 s0, s73, 0
	v_and_b32_e32 v114, 0x78, v4
	v_bitop3_b32 v4, v1, v0, 24 bitop3:0x36
	v_writelane_b32 v243, s0, 25
	s_add_u32 s0, s72, 0xe300000
	v_lshlrev_b32_e32 v4, 3, v4
	v_writelane_b32 v243, s0, 26
	s_addc_u32 s0, s73, 0
	v_and_b32_e32 v116, 0x78, v4
	v_bitop3_b32 v4, v1, v0, 28 bitop3:0x36
	v_writelane_b32 v243, s0, 27
	s_add_u32 s0, s72, 0x19d00000
	v_and_b32_e32 v3, 15, v0
	v_lshlrev_b32_e32 v4, 3, v4
	v_writelane_b32 v243, s0, 28
	s_addc_u32 s0, s73, 0
	v_bfe_u32 v2, v0, 5, 1
	v_and_b32_e32 v118, 0x78, v4
	v_lshlrev_b32_e32 v4, 5, v1
	v_lshlrev_b32_e32 v5, 3, v3
	v_writelane_b32 v243, s0, 29
	s_add_u32 s0, s72, 0x19b00000
	v_xor_b32_e32 v120, v4, v5
	v_bitop3_b32 v5, v2, v0, 15 bitop3:0x78
	v_writelane_b32 v243, s0, 30
	s_addc_u32 s0, s73, 0
	v_lshlrev_b32_e32 v119, 4, v5
	v_bitop3_b32 v5, v2, v3, 2 bitop3:0x36
	v_writelane_b32 v243, s0, 31
	v_lshlrev_b32_e32 v121, 4, v5
	v_bitop3_b32 v5, v2, v3, 4 bitop3:0x36
	v_readlane_b32 s6, v243, 9
	v_lshlrev_b32_e32 v142, 4, v5
	v_bitop3_b32 v5, v2, v3, 6 bitop3:0x36
	s_lshl_b32 s0, s6, 3
	v_readlane_b32 s5, v243, 0
	v_lshlrev_b32_e32 v143, 4, v5
	v_bitop3_b32 v5, v2, v3, 8 bitop3:0x36
	s_add_i32 s12, s0, s5
	v_readlane_b32 s0, v243, 1
	v_and_b32_e32 v100, 31, v0
	v_lshlrev_b32_e32 v144, 4, v5
	v_bitop3_b32 v5, v2, v3, 10 bitop3:0x36
	s_bfe_u32 s1, s0, 0x20006
	v_lshlrev_b32_e32 v102, 3, v2
	v_lshlrev_b32_e32 v122, 2, v2
	v_or_b32_e32 v4, 0x80, v100
	v_lshlrev_b32_e32 v145, 4, v5
	v_bitop3_b32 v5, v2, v3, 12 bitop3:0x36
	v_bitop3_b32 v2, v2, v3, 14 bitop3:0x36
	v_readlane_b32 s7, v243, 10
	v_writelane_b32 v243, s1, 32
	s_bfe_u32 s0, s0, 0x10008
	v_lshlrev_b32_e32 v147, 4, v2
	v_sub_u32_e32 v2, v4, v122
	s_movk_i32 s1, 0x7f
	v_writelane_b32 v243, s0, 33
	v_cmp_lt_u32_e64 s[8:9], s1, v2
	v_sub_u32_e32 v3, v122, v4
	s_movk_i32 s4, 0xff80
	v_writelane_b32 v243, s8, 34
	v_sub_u32_e32 v4, v100, v122
	v_lshlrev_b32_e32 v146, 4, v5
	v_writelane_b32 v243, s9, 35
	v_cmp_gt_u32_e64 s[8:9], s4, v3
	v_add_u32_e32 v5, 0x7e, v4
	v_add_u32_e32 v6, 0x7d, v4
	v_writelane_b32 v243, s8, 36
	v_add_u32_e32 v7, 0x78, v4
	v_add_u32_e32 v8, 0x77, v4
	v_writelane_b32 v243, s9, 37
	v_cmp_lt_u32_e64 s[8:9], s1, v5
	v_add_u32_e32 v9, 0x76, v4
	v_add_u32_e32 v10, 0x75, v4
	v_writelane_b32 v243, s8, 38
	v_add_u32_e32 v11, 0x70, v4
	v_add_u32_e32 v12, 0x6f, v4
	v_writelane_b32 v243, s9, 39
	v_cmp_lt_u32_e64 s[8:9], s1, v6
	v_add_u32_e32 v13, 0x6e, v4
	v_add_u32_e32 v14, 0x6d, v4
	v_writelane_b32 v243, s8, 40
	v_add_u32_e32 v15, 0x68, v4
	v_add_u32_e32 v16, 0x67, v4
	v_writelane_b32 v243, s9, 41
	v_cmp_lt_u32_e64 s[8:9], s1, v7
	v_add_u32_e32 v17, 0x66, v4
	v_add_u32_e32 v4, 0x65, v4
	v_writelane_b32 v243, s8, 42
	s_movk_i32 s0, 0x80
	v_or_b32_e32 v18, 2, v122
	v_writelane_b32 v243, s9, 43
	v_cmp_lt_u32_e64 s[8:9], s1, v8
	v_cmp_gt_u32_e64 s[42:43], v18, v100
	v_or_b32_e32 v18, 3, v122
	v_writelane_b32 v243, s8, 44
	v_cmp_gt_u32_e64 s[44:45], v18, v100
	v_or_b32_e32 v18, 8, v122
	v_writelane_b32 v243, s9, 45
	v_cmp_lt_u32_e64 s[8:9], s1, v9
	v_cmp_gt_u32_e64 s[46:47], v18, v100
	v_or_b32_e32 v18, 9, v122
	v_writelane_b32 v243, s8, 46
	v_cmp_gt_u32_e64 s[48:49], v18, v100
	v_or_b32_e32 v18, 10, v122
	v_writelane_b32 v243, s9, 47
	v_cmp_lt_u32_e64 s[8:9], s1, v10
	v_cmp_gt_u32_e64 s[50:51], v18, v100
	v_or_b32_e32 v18, 11, v122
	v_writelane_b32 v243, s8, 48
	v_cmp_gt_u32_e64 s[52:53], v18, v100
	v_or_b32_e32 v18, 16, v122
	v_writelane_b32 v243, s9, 49
	v_cmp_lt_u32_e64 s[8:9], s1, v11
	v_cmp_gt_u32_e64 s[54:55], v18, v100
	v_or_b32_e32 v18, 17, v122
	v_writelane_b32 v243, s8, 50
	v_cmp_gt_u32_e64 s[56:57], v18, v100
	v_or_b32_e32 v18, 18, v122
	v_writelane_b32 v243, s9, 51
	v_cmp_lt_u32_e64 s[8:9], s1, v12
	v_cmp_gt_u32_e64 s[58:59], v18, v100
	v_or_b32_e32 v18, 19, v122
	v_writelane_b32 v243, s8, 52
	v_cmp_gt_u32_e64 s[60:61], v18, v100
	v_or_b32_e32 v18, 24, v122
	v_writelane_b32 v243, s9, 53
	v_cmp_lt_u32_e64 s[8:9], s1, v13
	v_and_b32_e32 v98, 63, v0
	v_cmp_gt_u32_e64 s[62:63], v18, v100
	v_writelane_b32 v243, s8, 54
	v_or_b32_e32 v18, 25, v122
	v_cmp_gt_u32_e64 s[64:65], v18, v100
	v_writelane_b32 v243, s9, 55
	v_cmp_lt_u32_e64 s[8:9], s1, v14
	v_or_b32_e32 v18, 26, v122
	v_cmp_gt_u32_e64 s[66:67], v18, v100
	v_writelane_b32 v243, s8, 56
	v_or_b32_e32 v18, 27, v122
	v_cmp_gt_u32_e64 s[68:69], v18, v100
	v_writelane_b32 v243, s9, 57
	v_cmp_lt_u32_e64 s[8:9], s1, v15
	v_bfe_u32 v18, v0, 2, 2
	v_lshrrev_b32_e32 v20, 3, v0
	v_writelane_b32 v243, s8, 58
	v_bfe_u32 v21, v0, 1, 1
	v_or_b32_e32 v19, v122, v18
	v_writelane_b32 v243, s9, 59
	v_cmp_lt_u32_e64 s[8:9], s1, v16
	v_and_or_b32 v20, v20, 2, v21
	v_lshlrev_b32_e32 v21, 3, v0
	v_writelane_b32 v243, s8, 60
	v_lshlrev_b32_e32 v20, 4, v20
	v_and_b32_e32 v21, 8, v21
	v_writelane_b32 v243, s9, 61
	v_cmp_lt_u32_e64 s[8:9], s1, v17
	v_mov_b32_e32 v105, 0
	v_lshlrev_b32_e32 v148, 6, v18
	v_writelane_b32 v243, s8, 62
	v_or_b32_e32 v103, 4, v1
	v_or_b32_e32 v107, 8, v1
	v_writelane_b32 v243, s9, 63
	v_cmp_lt_u32_e64 s[8:9], s1, v4
	s_movk_i32 s1, 0xff7f
	v_or_b32_e32 v109, 12, v1
	v_writelane_b32 v242, s8, 0
	v_or_b32_e32 v111, 16, v1
	v_or_b32_e32 v113, 20, v1
	v_writelane_b32 v242, s9, 1
	v_cmp_lt_u32_e64 s[8:9], s0, v2
	v_or_b32_e32 v115, 24, v1
	v_or_b32_e32 v117, 28, v1
	v_writelane_b32 v242, s8, 2
	v_cmp_lt_u32_e64 s[38:39], v100, v122
	v_cmp_gt_u32_e64 s[40:41], v100, v122
	v_writelane_b32 v242, s9, 3
	v_cmp_gt_u32_e64 s[8:9], s1, v3
	v_xor_b32_e32 v149, 64, v148
	v_xor_b32_e32 v150, 0x80, v148
	v_writelane_b32 v242, s8, 4
	v_xor_b32_e32 v151, 0xc0, v148
	v_lshlrev_b32_e32 v124, 10, v100
	v_writelane_b32 v242, s9, 5
	v_cmp_lt_u32_e64 s[8:9], s0, v5
	v_mov_b32_e32 v125, v105
	v_mov_b32_e32 v123, v105
	v_writelane_b32 v242, s8, 6
	v_mov_b32_e32 v101, v105
	v_mov_b32_e32 v99, v105
	v_writelane_b32 v242, s9, 7
	v_cmp_lt_u32_e64 s[8:9], s0, v6
	s_mov_b64 s[80:81], 0xc00
	s_mov_b64 s[82:83], 0x1000
	v_writelane_b32 v242, s8, 8
	s_mov_b64 s[84:85], 0x1400
	s_mov_b64 s[86:87], 0x1800
	v_writelane_b32 v242, s9, 9
	v_cmp_lt_u32_e64 s[8:9], s0, v7
	s_mov_b64 s[88:89], 0x1c00
	s_mov_b32 s90, 0x3e0293ee
	v_writelane_b32 v242, s8, 10
	s_movk_i32 s76, 0x7fff
	v_mov_b32_e32 v154, 0xff800000
	v_writelane_b32 v242, s9, 11
	v_cmp_lt_u32_e64 s[8:9], s0, v8
	v_mov_b32_e32 v156, 0x43e00000
	v_mov_b32_e32 v157, 1
	v_writelane_b32 v242, s8, 12
	s_nop 1
	v_writelane_b32 v242, s9, 13
	v_cmp_lt_u32_e64 s[8:9], s0, v9
	s_nop 1
	v_writelane_b32 v242, s8, 14
	s_nop 1
	v_writelane_b32 v242, s9, 15
	v_cmp_lt_u32_e64 s[8:9], s0, v10
	s_nop 1
	v_writelane_b32 v242, s8, 16
	s_nop 1
	v_writelane_b32 v242, s9, 17
	v_cmp_lt_u32_e64 s[8:9], s0, v11
	s_nop 1
	v_writelane_b32 v242, s8, 18
	s_nop 1
	v_writelane_b32 v242, s9, 19
	v_cmp_lt_u32_e64 s[8:9], s0, v12
	s_nop 1
	v_writelane_b32 v242, s8, 20
	s_nop 1
	v_writelane_b32 v242, s9, 21
	v_cmp_lt_u32_e64 s[8:9], s0, v13
	s_nop 1
	v_writelane_b32 v242, s8, 22
	s_nop 1
	v_writelane_b32 v242, s9, 23
	v_cmp_lt_u32_e64 s[8:9], s0, v14
	s_nop 1
	v_writelane_b32 v242, s8, 24
	s_nop 1
	v_writelane_b32 v242, s9, 25
	v_cmp_lt_u32_e64 s[8:9], s0, v15
	s_nop 1
	v_writelane_b32 v242, s8, 26
	s_nop 1
	v_writelane_b32 v242, s9, 27
	v_cmp_lt_u32_e64 s[8:9], s0, v16
	s_nop 1
	v_writelane_b32 v242, s8, 28
	s_nop 1
	v_writelane_b32 v242, s9, 29
	v_cmp_lt_u32_e64 s[8:9], s0, v17
	v_cmp_lt_u32_e64 s[0:1], s0, v4
	s_nop 0
	v_writelane_b32 v242, s8, 30
	s_nop 1
	v_writelane_b32 v242, s9, 31
	v_writelane_b32 v242, s0, 32
	s_nop 1
	v_writelane_b32 v242, s1, 33
	v_cmp_gt_u32_e64 s[0:1], 32, v98
	s_nop 1
	v_writelane_b32 v242, s0, 34
	s_nop 1
	v_writelane_b32 v242, s1, 35
	s_lshl_b32 s0, s5, 14
	s_add_i32 s15, s0, 0
	v_lshl_add_u32 v2, v19, 8, s15
	v_add3_u32 v153, v2, v20, v21
	s_lshl_b32 s0, s6, 8
	s_lshl_b32 s1, s5, 5
	v_mbcnt_lo_u32_b32 v2, -1, 0
	v_lshl_add_u32 v152, v100, 8, s15
	s_add_i32 s33, s15, 0x2000
	s_add_i32 s91, s15, 0x400
	s_add_i32 s26, s15, 0x800
	s_add_i32 s27, s15, 0xc00
	s_add_i32 s28, s15, 0x1000
	s_add_i32 s29, s15, 0x1400
	s_add_i32 s30, s15, 0x1800
	s_add_i32 s31, s15, 0x1c00
	s_add_i32 s34, s15, 0x2400
	s_add_i32 s35, s15, 0x2800
	s_add_i32 s36, s15, 0x2c00
	s_add_i32 s37, s15, 0x3000
	s_add_i32 s16, s15, 0x3400
	s_add_i32 s17, s15, 0x3800
	s_add_i32 s13, s15, 0x3c00
	s_add_i32 s14, s0, s1
	s_lshl_b32 s0, s18, 8
	s_mov_b32 s1, 0xc3e00000
	v_mbcnt_hi_u32_b32 v155, -1, v2
	s_and_b32 s5, s5, 1
	s_cmp_eq_u32 s5, 0
	s_cbranch_scc1 .Lmy_p2stg_done
.Lmy_p2stg_loop:
	s_sleep 56
	s_add_i32 s5, s5, -1
	s_cmp_lg_u32 s5, 0
	s_cbranch_scc1 .Lmy_p2stg_loop
.Lmy_p2stg_done:
	s_branch .LBB0_218
.LBB0_216:
	s_or_b64 exec, exec, s[6:7]

.LBB0_218:
	s_cmpk_gt_i32 s12, 0x27ff
	s_cbranch_scc1 .LBB0_217
	s_mov_b64 s[4:5], -1
	s_cmpk_gt_i32 s12, 0x17ff
	v_lshlrev_b32_e32 v138, 1, v102
	v_lshlrev_b32_e32 v104, 1, v106
	v_lshlrev_b32_e32 v136, 1, v108
	v_lshlrev_b32_e32 v134, 1, v110
	v_lshlrev_b32_e32 v132, 1, v112
	v_lshlrev_b32_e32 v130, 1, v114
	v_lshlrev_b32_e32 v128, 1, v116
	v_lshlrev_b32_e32 v126, 1, v118
	s_cbranch_scc0 .LBB0_256
	s_sub_i32 s5, s12, s3
	s_cmpk_gt_i32 s5, 0x17ff
	s_cbranch_scc1 .Lmy_p2_nobar
	s_barrier
.Lmy_p2_nobar:
	s_lshr_b32 s5, s12, 7
	s_add_i32 s4, s12, 0xffffe800
	s_and_b32 s5, s5, 4
	v_readlane_b32 s6, v243, 32
	s_or_b32 s77, s5, s6
	s_lshr_b32 s5, s12, 2
	s_lshr_b32 s10, s4, 10
	s_and_b32 s94, s5, 0x7e
	v_readlane_b32 s5, v243, 33
	s_lshl_b32 s4, s10, 3
	s_or_b32 s78, s94, s5
	s_or_b32 s4, s4, s77
	s_mov_b32 s5, s25
	s_lshl_b32 s6, s10, 1
	s_bfe_u32 s7, s12, 0x10009
	s_lshl_b32 s11, s78, 5
	s_or_b32 s24, s6, s7
	s_lshl_b64 s[4:5], s[4:5], 20
	v_readlane_b32 s6, v243, 22
	s_add_u32 s4, s6, s4
	v_readlane_b32 s6, v243, 23
	s_addc_u32 s5, s6, s5
	s_lshl_b64 s[6:7], s[24:25], 20
	v_readlane_b32 s8, v243, 24
	s_add_u32 s8, s8, s6
	v_readlane_b32 s6, v243, 25
	s_addc_u32 s9, s6, s7
	s_lshl_b32 s6, s77, 2
	s_add_u32 s6, s22, s6
	s_addc_u32 s7, s23, 0
	v_mov_b64_e32 v[2:3], s[6:7]
	flat_load_dword v158, v[2:3]
	v_or_b32_e32 v2, s11, v100
	v_lshlrev_b32_e32 v2, 8, v2
	v_mov_b32_e32 v3, v105
	v_lshl_add_u64 v[2:3], s[4:5], 0, v[2:3]
	v_mov_b32_e32 v139, v105
	v_lshl_add_u64 v[2:3], v[2:3], 0, v[138:139]
	global_load_dwordx4 v[50:53], v[2:3], off
	global_load_dwordx4 v[90:93], v[2:3], off offset:32
	global_load_dwordx4 v[86:89], v[2:3], off offset:64
	global_load_dwordx4 v[82:85], v[2:3], off offset:96
	global_load_dwordx4 v[78:81], v[2:3], off offset:128
	global_load_dwordx4 v[74:77], v[2:3], off offset:160
	global_load_dwordx4 v[70:73], v[2:3], off offset:192
	global_load_dwordx4 v[66:69], v[2:3], off offset:224
	s_sub_i32 s79, 4, s78
	s_cmp_gt_u32 s94, 3
	s_cselect_b64 s[4:5], -1, 0
	s_and_b64 s[6:7], s[4:5], exec
	s_cselect_b32 s6, 0, s79
	s_add_i32 s79, s11, 0xffffff80
	s_lshl_b32 s92, s6, 5
	s_add_i32 s92, s92, s79
	v_or_b32_e32 v2, s92, v1
	v_ashrrev_i32_e32 v3, 31, v2
	v_lshlrev_b64 v[2:3], 8, v[2:3]
	s_lshl_b32 s7, s6, 13
	v_lshl_add_u64 v[2:3], s[8:9], 0, v[2:3]
	s_waitcnt lgkmcnt(0)
	s_and_b32 s7, s7, 0x2000
	v_lshl_add_u64 v[2:3], v[2:3], 0, v[104:105]
	s_add_i32 s7, s7, s15
	s_mov_b32 s93, m0
	s_mov_b32 m0, s7
	s_nop 0
	global_load_lds_dwordx4 v[2:3], off
	s_mov_b32 m0, s93
	v_or_b32_e32 v2, s92, v103
	v_ashrrev_i32_e32 v3, 31, v2
	v_lshlrev_b64 v[2:3], 8, v[2:3]
	v_lshl_add_u64 v[2:3], s[8:9], 0, v[2:3]
	v_mov_b32_e32 v137, v105
	v_lshl_add_u64 v[2:3], v[2:3], 0, v[136:137]
	s_add_i32 s93, s7, 0x400
	s_mov_b32 s95, m0
	s_mov_b32 m0, s93
	s_nop 0
	global_load_lds_dwordx4 v[2:3], off
	s_mov_b32 m0, s95
	v_or_b32_e32 v2, s92, v107
	v_ashrrev_i32_e32 v3, 31, v2
	v_lshlrev_b64 v[2:3], 8, v[2:3]
	v_lshl_add_u64 v[2:3], s[8:9], 0, v[2:3]
	v_mov_b32_e32 v135, v105
	v_lshl_add_u64 v[2:3], v[2:3], 0, v[134:135]
	s_add_i32 s93, s7, 0x800
	s_mov_b32 s95, m0
	s_mov_b32 m0, s93
	s_nop 0
	global_load_lds_dwordx4 v[2:3], off
	s_mov_b32 m0, s95
	v_or_b32_e32 v2, s92, v109
	v_ashrrev_i32_e32 v3, 31, v2
	v_lshlrev_b64 v[2:3], 8, v[2:3]
	v_lshl_add_u64 v[2:3], s[8:9], 0, v[2:3]
	v_mov_b32_e32 v133, v105
	v_lshl_add_u64 v[2:3], v[2:3], 0, v[132:133]
	s_add_i32 s93, s7, 0xc00
	s_mov_b32 s95, m0
	s_mov_b32 m0, s93
	s_nop 0
	global_load_lds_dwordx4 v[2:3], off
	s_mov_b32 m0, s95
	v_or_b32_e32 v2, s92, v111
	v_ashrrev_i32_e32 v3, 31, v2
	v_lshlrev_b64 v[2:3], 8, v[2:3]
	v_lshl_add_u64 v[2:3], s[8:9], 0, v[2:3]
	v_lshl_add_u64 v[2:3], v[2:3], 0, v[104:105]
	s_add_i32 s93, s7, 0x1000
	s_mov_b32 s95, m0
	s_mov_b32 m0, s93
	s_nop 0
	global_load_lds_dwordx4 v[2:3], off
	s_mov_b32 m0, s95
	v_or_b32_e32 v2, s92, v113
	v_ashrrev_i32_e32 v3, 31, v2
	v_lshlrev_b64 v[2:3], 8, v[2:3]
	v_lshl_add_u64 v[2:3], s[8:9], 0, v[2:3]
	v_mov_b32_e32 v131, v105
	v_lshl_add_u64 v[2:3], v[2:3], 0, v[130:131]
	s_add_i32 s93, s7, 0x1400
	s_mov_b32 s95, m0
	s_mov_b32 m0, s93
	s_nop 0
	global_load_lds_dwordx4 v[2:3], off
	s_mov_b32 m0, s95
	v_or_b32_e32 v2, s92, v115
	v_ashrrev_i32_e32 v3, 31, v2
	v_lshlrev_b64 v[2:3], 8, v[2:3]
	v_lshl_add_u64 v[2:3], s[8:9], 0, v[2:3]
	v_mov_b32_e32 v129, v105
	v_lshl_add_u64 v[2:3], v[2:3], 0, v[128:129]
	s_add_i32 s93, s7, 0x1800
	s_mov_b32 s95, m0
	s_mov_b32 m0, s93
	s_nop 0
	global_load_lds_dwordx4 v[2:3], off
	s_mov_b32 m0, s95
	v_or_b32_e32 v2, s92, v117
	v_ashrrev_i32_e32 v3, 31, v2
	v_lshlrev_b64 v[2:3], 8, v[2:3]
	v_lshl_add_u64 v[2:3], s[8:9], 0, v[2:3]
	v_mov_b32_e32 v127, v105
	v_lshl_add_u64 v[2:3], v[2:3], 0, v[126:127]
	s_addk_i32 s7, 0x1c00
	s_mov_b32 s92, m0
	s_mov_b32 m0, s7
	s_nop 0
	global_load_lds_dwordx4 v[2:3], off
	s_mov_b32 m0, s92
	s_cmp_gt_i32 s6, 3
	s_cbranch_scc1 .LBB0_222
	s_add_i32 s6, s6, 1
	s_lshl_b32 s7, s6, 13
	s_lshl_b32 s6, s6, 5
	s_add_i32 s6, s6, s79
	v_or_b32_e32 v2, s6, v1
	v_ashrrev_i32_e32 v3, 31, v2
	v_lshlrev_b64 v[2:3], 8, v[2:3]
	v_lshl_add_u64 v[2:3], s[8:9], 0, v[2:3]
	s_and_b32 s7, s7, 0x2000
	v_lshl_add_u64 v[2:3], v[2:3], 0, v[104:105]
	s_add_i32 s7, s7, s15
	s_mov_b32 s92, m0
	s_mov_b32 m0, s7
	s_nop 0
	global_load_lds_dwordx4 v[2:3], off
	s_mov_b32 m0, s92
	v_or_b32_e32 v2, s6, v103
	v_ashrrev_i32_e32 v3, 31, v2
	v_lshlrev_b64 v[2:3], 8, v[2:3]
	v_lshl_add_u64 v[2:3], s[8:9], 0, v[2:3]
	v_lshl_add_u64 v[2:3], v[2:3], 0, v[136:137]
	s_add_i32 s92, s7, 0x400
	s_mov_b32 s93, m0
	s_mov_b32 m0, s92
	s_nop 0
	global_load_lds_dwordx4 v[2:3], off
	s_mov_b32 m0, s93
	v_or_b32_e32 v2, s6, v107
	v_ashrrev_i32_e32 v3, 31, v2
	v_lshlrev_b64 v[2:3], 8, v[2:3]
	v_lshl_add_u64 v[2:3], s[8:9], 0, v[2:3]
	v_lshl_add_u64 v[2:3], v[2:3], 0, v[134:135]
	s_add_i32 s92, s7, 0x800
	s_mov_b32 s93, m0
	s_mov_b32 m0, s92
	s_nop 0
	global_load_lds_dwordx4 v[2:3], off
	s_mov_b32 m0, s93
	v_or_b32_e32 v2, s6, v109
	v_ashrrev_i32_e32 v3, 31, v2
	v_lshlrev_b64 v[2:3], 8, v[2:3]
	v_lshl_add_u64 v[2:3], s[8:9], 0, v[2:3]
	v_lshl_add_u64 v[2:3], v[2:3], 0, v[132:133]
	s_add_i32 s92, s7, 0xc00
	s_mov_b32 s93, m0
	s_mov_b32 m0, s92
	s_nop 0
	global_load_lds_dwordx4 v[2:3], off
	s_mov_b32 m0, s93
	v_or_b32_e32 v2, s6, v111
	v_ashrrev_i32_e32 v3, 31, v2
	v_lshlrev_b64 v[2:3], 8, v[2:3]
	v_lshl_add_u64 v[2:3], s[8:9], 0, v[2:3]
	v_lshl_add_u64 v[2:3], v[2:3], 0, v[104:105]
	s_add_i32 s92, s7, 0x1000
	s_mov_b32 s93, m0
	s_mov_b32 m0, s92
	s_nop 0
	global_load_lds_dwordx4 v[2:3], off
	s_mov_b32 m0, s93
	v_or_b32_e32 v2, s6, v113
	v_ashrrev_i32_e32 v3, 31, v2
	v_lshlrev_b64 v[2:3], 8, v[2:3]
	v_lshl_add_u64 v[2:3], s[8:9], 0, v[2:3]
	v_lshl_add_u64 v[2:3], v[2:3], 0, v[130:131]
	s_add_i32 s92, s7, 0x1400
	s_mov_b32 s93, m0
	s_mov_b32 m0, s92
	s_nop 0
	global_load_lds_dwordx4 v[2:3], off
	s_mov_b32 m0, s93
	v_or_b32_e32 v2, s6, v115
	v_ashrrev_i32_e32 v3, 31, v2
	v_lshlrev_b64 v[2:3], 8, v[2:3]
	v_lshl_add_u64 v[2:3], s[8:9], 0, v[2:3]
	v_lshl_add_u64 v[2:3], v[2:3], 0, v[128:129]
	s_add_i32 s92, s7, 0x1800
	s_mov_b32 s93, m0
	s_mov_b32 m0, s92
	s_nop 0
	global_load_lds_dwordx4 v[2:3], off
	s_mov_b32 m0, s93
	v_or_b32_e32 v2, s6, v117
	v_ashrrev_i32_e32 v3, 31, v2
	v_lshlrev_b64 v[2:3], 8, v[2:3]
	v_lshl_add_u64 v[2:3], s[8:9], 0, v[2:3]
	v_lshl_add_u64 v[2:3], v[2:3], 0, v[126:127]
	s_addk_i32 s7, 0x1c00
	s_mov_b32 s6, m0
	s_mov_b32 m0, s7
	s_nop 0
	global_load_lds_dwordx4 v[2:3], off
	s_mov_b32 m0, s6
